# dilated attention pattern-combine stages: the 8 serialized partial-result reloads per stage batched (4 loads in flight per group, renamed into free registers)
# baseline (speedup 1.0000x reference)
; __device__ __forceinline__ unsigned cvt_pk_bf16(float lo, float hi) { unsigned r; asm volatile("v_cvt_pk_bf16_f32 %0, %1, %2" : "=v"(r) : "v"(lo), "v"(hi)); return r; }
; template <int P_>
; __device__ __forceinline__ void dil_wave_unit(LAS unsigned char* wl, const bf16_t* DIL, bf16_t* Y, bf16_t* ST, float* LSE, const float* BT, int b, int h, int r, int nb) {
;     ...
;     float lp[2]; u32x2 pv[2][8];
;     if (!first) {
; #pragma unroll
;         for (int qh = 0; qh < 2; ++qh) { const size_t srow = (size_t)(b * 8 + h) * SEQ + (size_t)(64 * nb + 32 * qh + r32) * dil + r; lp[qh] = LSE[srow];
;             const bf16_t* spb = ST + srow * 64;
; #pragma unroll
;             for (int e = 0; e < 8; e += 2) { const u32x4 L = *(const u32x4*)(spb + 32 * (e >> 2) + 8 * ((e & 3) + hi));
;                 u32x2 snd; snd.x = hi ? L.x : L.z; snd.y = hi ? L.y : L.w; u32x2 rcv; rcv.x = __shfl_xor(snd.x, 32); rcv.y = __shfl_xor(snd.y, 32);
;                 if (hi) { pv[qh][e] = rcv; pv[qh][e + 1].x = L.z; pv[qh][e + 1].y = L.w; } else { pv[qh][e].x = L.x; pv[qh][e].y = L.y; pv[qh][e + 1] = rcv; } } }
;     }
; #pragma unroll
;     for (int qh = 0; qh < 2; ++qh) {
;         const size_t spos = (size_t)(64 * nb + 32 * qh + r32) * dil + r; const size_t srow = (size_t)(b * 8 + h) * SEQ + spos;
;         const float lt = l_run[qh] + __shfl_xor(l_run[qh], 32); const float inv = 1.0f / lt; const float lse2 = m_run[qh] + __builtin_amdgcn_logf(lt);
;         float a_prev = 0.f, a_cur = inv, lse_new = lse2;
;         if (!first) { const float M = fmaxf(lp[qh], lse2); const float wp = __builtin_amdgcn_exp2f(lp[qh] - M), wc = __builtin_amdgcn_exp2f(lse2 - M); const float den = wp + wc;
;             a_prev = wp / den; a_cur = wc / den * inv; lse_new = M + __builtin_amdgcn_logf(den); }
;         bf16_t* ypb = last ? Y + (tok0 + spos) * 1024 + 512 + h * 64 : ST + srow * 64;
;         u32x2 wv[8];
; #pragma unroll
;         for (int e = 0; e < 8; ++e) { const int blk = e >> 2, g = e & 3;
;             float v0 = o[qh][blk][4 * g] * a_cur, v1 = o[qh][blk][4 * g + 1] * a_cur, v2 = o[qh][blk][4 * g + 2] * a_cur, v3 = o[qh][blk][4 * g + 3] * a_cur;
;             if (!first) { v0 += a_prev * bf_lo(pv[qh][e].x); v1 += a_prev * bf_hi(pv[qh][e].x); v2 += a_prev * bf_lo(pv[qh][e].y); v3 += a_prev * bf_hi(pv[qh][e].y); }
;             wv[e].x = cvt_pk_bf16(v0, v1); wv[e].y = cvt_pk_bf16(v2, v3); }
.LBB0_456:
	v_lshl_or_b32 v0, v210, 2, s82
	v_or_b32_e32 v70, s18, v0
	v_mov_b32_e32 v71, s19
	v_lshl_add_u64 v[66:67], v[70:71], 0, s[2:3]
	v_lshl_add_u64 v[68:69], v[66:67], 2, s[14:15]
	v_lshlrev_b64 v[66:67], 7, v[66:67]
	v_lshl_add_u64 v[66:67], s[12:13], 0, v[66:67]
	v_mov_b32_e32 v157, v1
	v_lshl_add_u64 v[84:85], v[66:67], 0, v[156:157]
	global_load_dword v93, v[68:69], off
	v_cmp_gt_u32_e64 s[40:41], 32, v209
	global_load_dwordx4 v[66:69], v[84:85], off
	global_load_dwordx4 v[240:243], v[84:85], off offset:32
	global_load_dwordx4 v[244:247], v[84:85], off offset:64
	global_load_dwordx4 v[248:251], v[84:85], off offset:96
	v_or_b32_e32 v86, 0x80, v0
	s_waitcnt vmcnt(0)
	v_cndmask_b32_e64 v70, v66, v68, s[40:41]
	v_cndmask_b32_e64 v72, v67, v69, s[40:41]
	ds_bpermute_b32 v70, v208, v70
	ds_bpermute_b32 v72, v208, v72
	s_waitcnt lgkmcnt(1)
	v_cndmask_b32_e64 v120, v68, v70, s[40:41]
	s_waitcnt lgkmcnt(0)
	v_cndmask_b32_e64 v117, v69, v72, s[40:41]
	v_cndmask_b32_e64 v122, v72, v67, s[40:41]
	v_cndmask_b32_e64 v92, v70, v66, s[40:41]
	v_lshlrev_b32_e32 v96, 16, v122
	v_lshlrev_b32_e32 v94, 16, v92
	v_and_b32_e32 v92, 0xffff0000, v92
	s_waitcnt vmcnt(0)
	v_cndmask_b32_e64 v70, v240, v242, s[40:41]
	v_cndmask_b32_e64 v72, v241, v243, s[40:41]
	ds_bpermute_b32 v70, v208, v70
	ds_bpermute_b32 v72, v208, v72
	s_waitcnt lgkmcnt(1)
	v_cndmask_b32_e64 v116, v242, v70, s[40:41]
	s_waitcnt lgkmcnt(0)
	v_cndmask_b32_e64 v113, v243, v72, s[40:41]
	v_cndmask_b32_e64 v119, v72, v241, s[40:41]
	v_cndmask_b32_e64 v121, v70, v240, s[40:41]
	s_waitcnt vmcnt(0)
	v_cndmask_b32_e64 v70, v244, v246, s[40:41]
	v_cndmask_b32_e64 v72, v245, v247, s[40:41]
	ds_bpermute_b32 v70, v208, v70
	ds_bpermute_b32 v72, v208, v72
	s_waitcnt lgkmcnt(1)
	v_cndmask_b32_e64 v112, v246, v70, s[40:41]
	s_waitcnt lgkmcnt(0)
	v_cndmask_b32_e64 v110, v247, v72, s[40:41]
	v_cndmask_b32_e64 v115, v72, v245, s[40:41]
	v_cndmask_b32_e64 v118, v70, v244, s[40:41]
	s_waitcnt vmcnt(0)
	v_cndmask_b32_e64 v70, v248, v250, s[40:41]
	v_cndmask_b32_e64 v72, v249, v251, s[40:41]
	ds_bpermute_b32 v70, v208, v70
	ds_bpermute_b32 v72, v208, v72
	s_waitcnt lgkmcnt(1)
	v_cndmask_b32_e64 v109, v250, v70, s[40:41]
	v_cndmask_b32_e64 v114, v70, v248, s[40:41]
	v_or_b32_e32 v70, s18, v86
	s_waitcnt lgkmcnt(0)
	v_cndmask_b32_e64 v111, v72, v249, s[40:41]
	v_lshl_add_u64 v[66:67], v[70:71], 0, s[2:3]
	v_cndmask_b32_e64 v87, v251, v72, s[40:41]
	v_lshl_add_u64 v[68:69], v[66:67], 2, s[14:15]
	v_lshlrev_b64 v[66:67], 7, v[66:67]
	v_lshl_add_u64 v[66:67], s[12:13], 0, v[66:67]
	v_lshl_add_u64 v[82:83], v[66:67], 0, v[156:157]
	global_load_dword v100, v[68:69], off
	s_nop 0
	global_load_dwordx4 v[66:69], v[82:83], off
	global_load_dwordx4 v[240:243], v[82:83], off offset:32
	global_load_dwordx4 v[244:247], v[82:83], off offset:64
	global_load_dwordx4 v[248:251], v[82:83], off offset:96
	s_waitcnt vmcnt(0)
	v_cndmask_b32_e64 v70, v66, v68, s[40:41]
	v_cndmask_b32_e64 v71, v67, v69, s[40:41]
	ds_bpermute_b32 v101, v208, v70
	ds_bpermute_b32 v102, v208, v71
	s_waitcnt vmcnt(0)
	v_cndmask_b32_e64 v74, v240, v242, s[40:41]
	v_cndmask_b32_e64 v75, v241, v243, s[40:41]
	ds_bpermute_b32 v103, v208, v74
	ds_bpermute_b32 v104, v208, v75
	s_waitcnt vmcnt(0)
	v_cndmask_b32_e64 v78, v244, v246, s[40:41]
	v_cndmask_b32_e64 v79, v245, v247, s[40:41]
	ds_bpermute_b32 v105, v208, v78
	ds_bpermute_b32 v106, v208, v79
	s_waitcnt vmcnt(0)
	v_cndmask_b32_e64 v88, v248, v250, s[40:41]
	v_cndmask_b32_e64 v89, v249, v251, s[40:41]
	ds_bpermute_b32 v107, v208, v88
	ds_bpermute_b32 v108, v208, v89
	v_lshl_add_u64 v[88:89], s[8:9], 0, v[0:1]
	ds_bpermute_b32 v0, v208, v154
	v_lshlrev_b64 v[90:91], 7, v[88:89]
	s_waitcnt lgkmcnt(0)
	v_add_f32_e32 v95, v154, v0
	v_log_f32_e32 v0, v95
	s_nop 0
	v_add_f32_e32 v97, v233, v0
	v_max_f32_e32 v0, v93, v93
	v_max_f32_e32 v0, v0, v97
	v_sub_f32_e32 v93, v93, v0
	v_sub_f32_e32 v97, v97, v0
	v_exp_f32_e32 v93, v93
	v_exp_f32_e32 v97, v97
	s_nop 0
	v_add_f32_e32 v123, v93, v97
	v_div_scale_f32 v98, s[34:35], v123, v123, v93
	v_rcp_f32_e32 v99, v98
	s_nop 0
	v_fma_f32 v124, -v98, v99, 1.0
	v_fmac_f32_e32 v99, v124, v99
	v_div_scale_f32 v124, vcc, v93, v123, v93
	v_mul_f32_e32 v125, v124, v99
	v_fma_f32 v126, -v98, v125, v124
	v_fmac_f32_e32 v125, v126, v99
	v_fma_f32 v98, -v98, v125, v124
	v_div_fmas_f32 v98, v98, v99, v125
	v_div_fixup_f32 v98, v98, v123, v93
	v_div_scale_f32 v93, s[34:35], v95, v95, 1.0
	v_rcp_f32_e32 v99, v93
	s_nop 0
	v_fma_f32 v124, -v93, v99, 1.0
	v_fmac_f32_e32 v99, v124, v99
	v_div_scale_f32 v124, vcc, 1.0, v95, 1.0
	v_mul_f32_e32 v125, v124, v99
	v_fma_f32 v126, -v93, v125, v124
	v_fmac_f32_e32 v125, v126, v99
	v_fma_f32 v93, -v93, v125, v124
	v_div_fmas_f32 v93, v93, v99, v125
	v_div_fixup_f32 v99, v93, v95, 1.0
	v_div_scale_f32 v93, s[34:35], v123, v123, v97
	v_rcp_f32_e32 v95, v93
	s_nop 0
	v_fma_f32 v124, -v93, v95, 1.0
	v_fmac_f32_e32 v95, v124, v95
	v_div_scale_f32 v124, vcc, v97, v123, v97
	v_mul_f32_e32 v125, v124, v95
	v_fma_f32 v126, -v93, v125, v124
	v_fmac_f32_e32 v125, v126, v95
	v_fma_f32 v93, -v93, v125, v124
	v_div_fmas_f32 v93, v93, v95, v125
	v_div_fixup_f32 v97, v93, v123, v97
	v_pk_mul_f32 v[96:97], v[98:99], v[96:97]
	v_mov_b32_e32 v99, v50
	v_mov_b32_e32 v95, v97
	v_pk_mul_f32 v[94:95], v[98:99], v[94:95]
	v_mov_b32_e32 v99, v51
	v_mov_b32_e32 v93, v97
	v_pk_mul_f32 v[50:51], v[98:99], v[92:93]
	v_fma_f32 v52, v52, v97, v96
	v_and_b32_e32 v96, 0xffff0000, v122
	v_mov_b32_e32 v99, v53
	v_add_f32_e32 v92, v50, v51
	v_pk_mul_f32 v[50:51], v[98:99], v[96:97]
	v_lshlrev_b32_e32 v96, 16, v120
	v_add_f32_e32 v50, v50, v51
	v_mov_b32_e32 v99, v54
; __device__ __forceinline__ unsigned cvt_pk_bf16(float lo, float hi) { unsigned r; asm volatile("v_cvt_pk_bf16_f32 %0, %1, %2" : "=v"(r) : "v"(lo), "v"(hi)); return r; }
; template <int P_>
; __device__ __forceinline__ void dil_wave_unit(LAS unsigned char* wl, const bf16_t* DIL, bf16_t* Y, bf16_t* ST, float* LSE, const float* BT, int b, int h, int r, int nb) {
;     ...
;         for (int e = 0; e < 8; ++e) { const int blk = e >> 2, g = e & 3;
;             float v0 = o[qh][blk][4 * g] * a_cur, v1 = o[qh][blk][4 * g + 1] * a_cur, v2 = o[qh][blk][4 * g + 2] * a_cur, v3 = o[qh][blk][4 * g + 3] * a_cur;
;             if (!first) { v0 += a_prev * bf_lo(pv[qh][e].x); v1 += a_prev * bf_hi(pv[qh][e].x); v2 += a_prev * bf_lo(pv[qh][e].y); v3 += a_prev * bf_hi(pv[qh][e].y); }
;             wv[e].x = cvt_pk_bf16(v0, v1); wv[e].y = cvt_pk_bf16(v2, v3); }
; #pragma unroll
;         for (int e = 0; e < 8; e += 2) { const u32x2 snd = hi ? wv[e] : wv[e + 1]; u32x2 rcv; rcv.x = __shfl_xor(snd.x, 32); rcv.y = __shfl_xor(snd.y, 32);
;             u32x4 o4; if (hi) { o4.x = rcv.x; o4.y = rcv.y; o4.z = wv[e + 1].x; o4.w = wv[e + 1].y; } else { o4.x = wv[e].x; o4.y = wv[e].y; o4.z = rcv.x; o4.w = rcv.y; }
;             *(u32x4*)(ypb + 32 * (e >> 2) + 8 * ((e & 3) + hi)) = o4; }
;         if (!last && hi == 0) LSE[srow] = lse_new;
	v_add_f32_e32 v94, v94, v95
	v_cvt_pk_bf16_f32 v53, v94, v92
	v_cvt_pk_bf16_f32 v52, v52, v50
	v_pk_mul_f32 v[50:51], v[98:99], v[96:97]
	v_and_b32_e32 v96, 0xffff0000, v120
	v_mov_b32_e32 v99, v55
	v_add_f32_e32 v54, v50, v51
	v_pk_mul_f32 v[50:51], v[98:99], v[96:97]
	v_lshlrev_b32_e32 v96, 16, v117
	v_mov_b32_e32 v99, v56
	v_add_f32_e32 v55, v50, v51
	v_pk_mul_f32 v[50:51], v[98:99], v[96:97]
	v_and_b32_e32 v96, 0xffff0000, v117
	v_mov_b32_e32 v99, v57
	v_add_f32_e32 v56, v50, v51
	v_pk_mul_f32 v[50:51], v[98:99], v[96:97]
	v_lshlrev_b32_e32 v96, 16, v121
	v_add_f32_e32 v50, v50, v51
	v_mov_b32_e32 v99, v58
	v_cvt_pk_bf16_f32 v54, v54, v55
	v_cvt_pk_bf16_f32 v55, v56, v50
	v_pk_mul_f32 v[50:51], v[98:99], v[96:97]
	v_and_b32_e32 v96, 0xffff0000, v121
	v_mov_b32_e32 v99, v59
	v_add_f32_e32 v56, v50, v51
	v_pk_mul_f32 v[50:51], v[98:99], v[96:97]
	v_lshlrev_b32_e32 v96, 16, v119
	v_mov_b32_e32 v99, v60
	v_add_f32_e32 v57, v50, v51
	v_pk_mul_f32 v[50:51], v[98:99], v[96:97]
	v_and_b32_e32 v96, 0xffff0000, v119
	v_mov_b32_e32 v99, v61
	v_add_f32_e32 v58, v50, v51
	v_pk_mul_f32 v[50:51], v[98:99], v[96:97]
	v_lshlrev_b32_e32 v96, 16, v116
	v_add_f32_e32 v50, v50, v51
	v_mov_b32_e32 v99, v62
	v_cvt_pk_bf16_f32 v56, v56, v57
	v_cvt_pk_bf16_f32 v57, v58, v50
	v_pk_mul_f32 v[50:51], v[98:99], v[96:97]
	v_and_b32_e32 v96, 0xffff0000, v116
	v_mov_b32_e32 v99, v63
	v_add_f32_e32 v58, v50, v51
	v_pk_mul_f32 v[50:51], v[98:99], v[96:97]
	v_lshlrev_b32_e32 v96, 16, v113
	v_mov_b32_e32 v99, v64
	v_add_f32_e32 v59, v50, v51
	v_pk_mul_f32 v[50:51], v[98:99], v[96:97]
	v_and_b32_e32 v96, 0xffff0000, v113
	v_mov_b32_e32 v99, v65
	v_add_f32_e32 v60, v50, v51
	v_pk_mul_f32 v[50:51], v[98:99], v[96:97]
	v_lshlrev_b32_e32 v96, 16, v118
	v_add_f32_e32 v50, v50, v51
	v_mov_b32_e32 v99, v34
	v_cvt_pk_bf16_f32 v58, v58, v59
	v_cvt_pk_bf16_f32 v59, v60, v50
	v_pk_mul_f32 v[50:51], v[98:99], v[96:97]
	v_and_b32_e32 v96, 0xffff0000, v118
	v_mov_b32_e32 v99, v35
	v_pk_mul_f32 v[34:35], v[98:99], v[96:97]
	v_lshlrev_b32_e32 v96, 16, v115
	v_mov_b32_e32 v99, v36
	v_add_f32_e32 v50, v50, v51
	v_add_f32_e32 v51, v34, v35
	v_pk_mul_f32 v[34:35], v[98:99], v[96:97]
	v_and_b32_e32 v96, 0xffff0000, v115
	v_mov_b32_e32 v99, v37
	v_add_f32_e32 v36, v34, v35
	v_pk_mul_f32 v[34:35], v[98:99], v[96:97]
	v_lshlrev_b32_e32 v96, 16, v112
	v_add_f32_e32 v34, v34, v35
	v_mov_b32_e32 v99, v38
	v_cvt_pk_bf16_f32 v50, v50, v51
	v_cvt_pk_bf16_f32 v51, v36, v34
	v_pk_mul_f32 v[34:35], v[98:99], v[96:97]
	v_and_b32_e32 v96, 0xffff0000, v112
	v_mov_b32_e32 v99, v39
	v_add_f32_e32 v36, v34, v35
	v_pk_mul_f32 v[34:35], v[98:99], v[96:97]
	v_lshlrev_b32_e32 v96, 16, v110
	v_mov_b32_e32 v99, v40
	v_add_f32_e32 v37, v34, v35
	v_pk_mul_f32 v[34:35], v[98:99], v[96:97]
	v_and_b32_e32 v96, 0xffff0000, v110
	v_mov_b32_e32 v99, v41
	v_add_f32_e32 v38, v34, v35
	v_pk_mul_f32 v[34:35], v[98:99], v[96:97]
	v_lshlrev_b32_e32 v96, 16, v114
	v_add_f32_e32 v34, v34, v35
	v_mov_b32_e32 v99, v42
	v_cvt_pk_bf16_f32 v40, v36, v37
	v_cvt_pk_bf16_f32 v41, v38, v34
	v_pk_mul_f32 v[34:35], v[98:99], v[96:97]
	v_and_b32_e32 v96, 0xffff0000, v114
	v_mov_b32_e32 v99, v43
	v_add_f32_e32 v36, v34, v35
	v_pk_mul_f32 v[34:35], v[98:99], v[96:97]
	v_lshlrev_b32_e32 v96, 16, v111
	v_mov_b32_e32 v99, v44
	v_add_f32_e32 v37, v34, v35
	v_pk_mul_f32 v[34:35], v[98:99], v[96:97]
	v_and_b32_e32 v96, 0xffff0000, v111
	v_mov_b32_e32 v99, v45
	v_add_f32_e32 v38, v34, v35
	v_pk_mul_f32 v[34:35], v[98:99], v[96:97]
	v_lshlrev_b32_e32 v96, 16, v109
	v_add_f32_e32 v34, v34, v35
	v_mov_b32_e32 v99, v46
	v_cvt_pk_bf16_f32 v42, v36, v37
	v_cvt_pk_bf16_f32 v43, v38, v34
	v_pk_mul_f32 v[34:35], v[98:99], v[96:97]
	v_and_b32_e32 v96, 0xffff0000, v109
	v_mov_b32_e32 v99, v47
	v_add_f32_e32 v36, v34, v35
	v_pk_mul_f32 v[34:35], v[98:99], v[96:97]
	v_lshlrev_b32_e32 v96, 16, v87
	v_mov_b32_e32 v99, v48
	v_add_f32_e32 v37, v34, v35
	v_pk_mul_f32 v[34:35], v[98:99], v[96:97]
	v_and_b32_e32 v96, 0xffff0000, v87
	v_mov_b32_e32 v99, v49
	v_add_f32_e32 v38, v34, v35
	v_pk_mul_f32 v[34:35], v[98:99], v[96:97]
	v_cvt_pk_bf16_f32 v44, v36, v37
	v_cndmask_b32_e64 v46, v57, v59, s[40:41]
	v_add_f32_e32 v34, v34, v35
	v_cvt_pk_bf16_f32 v45, v38, v34
	v_cndmask_b32_e64 v34, v53, v54, s[40:41]
	v_cndmask_b32_e64 v35, v52, v55, s[40:41]
	ds_bpermute_b32 v34, v208, v34
	ds_bpermute_b32 v35, v208, v35
	v_cndmask_b32_e64 v47, v56, v58, s[40:41]
	v_lshl_add_u64 v[38:39], s[12:13], 0, v[90:91]
	v_lshl_add_u64 v[38:39], v[38:39], 0, v[156:157]
	s_waitcnt lgkmcnt(1)
	v_cndmask_b32_e64 v36, v54, v34, s[40:41]
	v_cndmask_b32_e64 v34, v34, v53, s[40:41]
	s_waitcnt lgkmcnt(0)
	v_cndmask_b32_e64 v37, v55, v35, s[40:41]
	v_cndmask_b32_e64 v35, v35, v52, s[40:41]
	global_store_dwordx4 v[84:85], v[34:37], off
	ds_bpermute_b32 v34, v208, v47
	ds_bpermute_b32 v35, v208, v46
	v_cndmask_b32_e64 v46, v51, v41, s[40:41]
	v_cndmask_b32_e64 v47, v50, v40, s[40:41]
	s_waitcnt lgkmcnt(1)
	v_cndmask_b32_e64 v36, v58, v34, s[40:41]
	v_cndmask_b32_e64 v34, v34, v56, s[40:41]
	s_waitcnt lgkmcnt(0)
	v_cndmask_b32_e64 v37, v59, v35, s[40:41]
	v_cndmask_b32_e64 v35, v35, v57, s[40:41]
	global_store_dwordx4 v[38:39], v[34:37], off offset:32
	ds_bpermute_b32 v34, v208, v47
	ds_bpermute_b32 v35, v208, v46
	v_cndmask_b32_e64 v46, v43, v45, s[40:41]
	v_cndmask_b32_e64 v47, v42, v44, s[40:41]
	s_waitcnt lgkmcnt(1)
	v_cndmask_b32_e64 v36, v40, v34, s[40:41]
	v_cndmask_b32_e64 v34, v34, v50, s[40:41]
	s_waitcnt lgkmcnt(0)
	v_cndmask_b32_e64 v37, v41, v35, s[40:41]
	v_cndmask_b32_e64 v35, v35, v51, s[40:41]
	global_store_dwordx4 v[84:85], v[34:37], off offset:64
	ds_bpermute_b32 v34, v208, v47
	ds_bpermute_b32 v35, v208, v46
	s_waitcnt lgkmcnt(1)
	v_cndmask_b32_e64 v36, v44, v34, s[40:41]
	v_cndmask_b32_e64 v34, v34, v42, s[40:41]
	s_waitcnt lgkmcnt(0)
	v_cndmask_b32_e64 v37, v45, v35, s[40:41]
	v_cndmask_b32_e64 v35, v35, v43, s[40:41]
	global_store_dwordx4 v[38:39], v[34:37], off offset:96
	s_and_saveexec_b64 s[34:35], s[40:41]
	s_cbranch_execz .LBB0_458
	v_log_f32_e32 v34, v123
	s_nop 0
	v_add_f32_e32 v0, v0, v34
	v_lshl_add_u64 v[34:35], v[88:89], 2, s[14:15]
	global_store_dword v[34:35], v0, off
; template <int P_>
; __device__ __forceinline__ void dil_wave_unit(LAS unsigned char* wl, const bf16_t* DIL, bf16_t* Y, bf16_t* ST, float* LSE, const float* BT, int b, int h, int r, int nb) {
;     ...
;                 u32x2 snd; snd.x = hi ? L.x : L.z; snd.y = hi ? L.y : L.w; u32x2 rcv; rcv.x = __shfl_xor(snd.x, 32); rcv.y = __shfl_xor(snd.y, 32);
;                 if (hi) { pv[qh][e] = rcv; pv[qh][e + 1].x = L.z; pv[qh][e + 1].y = L.w; } else { pv[qh][e].x = L.x; pv[qh][e].y = L.y; pv[qh][e + 1] = rcv; } } }
;     }
; #pragma unroll
;     for (int qh = 0; qh < 2; ++qh) {
;         const size_t spos = (size_t)(64 * nb + 32 * qh + r32) * dil + r; const size_t srow = (size_t)(b * 8 + h) * SEQ + spos;
;         const float lt = l_run[qh] + __shfl_xor(l_run[qh], 32); const float inv = 1.0f / lt; const float lse2 = m_run[qh] + __builtin_amdgcn_logf(lt);
;         float a_prev = 0.f, a_cur = inv, lse_new = lse2;
;         if (!first) { const float M = fmaxf(lp[qh], lse2); const float wp = __builtin_amdgcn_exp2f(lp[qh] - M), wc = __builtin_amdgcn_exp2f(lse2 - M); const float den = wp + wc;
;             a_prev = wp / den; a_cur = wc / den * inv; lse_new = M + __builtin_amdgcn_logf(den); }
;         bf16_t* ypb = last ? Y + (tok0 + spos) * 1024 + 512 + h * 64 : ST + srow * 64;
;         u32x2 wv[8];
; #pragma unroll
;         for (int e = 0; e < 8; ++e) { const int blk = e >> 2, g = e & 3;
;             float v0 = o[qh][blk][4 * g] * a_cur, v1 = o[qh][blk][4 * g + 1] * a_cur, v2 = o[qh][blk][4 * g + 2] * a_cur, v3 = o[qh][blk][4 * g + 3] * a_cur;
;             if (!first) { v0 += a_prev * bf_lo(pv[qh][e].x); v1 += a_prev * bf_hi(pv[qh][e].x); v2 += a_prev * bf_lo(pv[qh][e].y); v3 += a_prev * bf_hi(pv[qh][e].y); }
.LBB0_458:
	s_or_b64 exec, exec, s[34:35]
	ds_bpermute_b32 v38, v208, v155
	v_cndmask_b32_e64 v0, v101, v66, s[40:41]
	v_lshlrev_b32_e32 v42, 16, v0
	v_and_b32_e32 v44, 0xffff0000, v0
	v_cndmask_b32_e64 v49, v102, v67, s[40:41]
	s_waitcnt lgkmcnt(0)
	v_add_f32_e32 v39, v155, v38
	v_log_f32_e32 v0, v39
	v_lshlrev_b32_e32 v46, 16, v49
	v_cndmask_b32_e64 v48, v68, v101, s[40:41]
	v_cndmask_b32_e64 v41, v69, v102, s[40:41]
	v_add_f32_e32 v38, v130, v0
	v_max_f32_e32 v0, v100, v100
	v_max_f32_e32 v0, v0, v38
	v_sub_f32_e32 v40, v100, v0
	v_sub_f32_e32 v38, v38, v0
	v_exp_f32_e32 v43, v40
	v_exp_f32_e32 v45, v38
	v_cndmask_b32_e64 v53, v103, v240, s[40:41]
	v_cndmask_b32_e64 v52, v104, v241, s[40:41]
	v_cndmask_b32_e64 v51, v242, v103, s[40:41]
	v_add_f32_e32 v40, v43, v45
	v_div_scale_f32 v38, s[34:35], v40, v40, v43
	v_rcp_f32_e32 v47, v38
	v_cndmask_b32_e64 v50, v243, v104, s[40:41]
	v_cndmask_b32_e64 v57, v105, v244, s[40:41]
	v_cndmask_b32_e64 v56, v106, v245, s[40:41]
	v_fma_f32 v62, -v38, v47, 1.0
	v_fmac_f32_e32 v47, v62, v47
	v_div_scale_f32 v62, vcc, v43, v40, v43
	v_mul_f32_e32 v63, v62, v47
	v_fma_f32 v64, -v38, v63, v62
	v_fmac_f32_e32 v63, v64, v47
	v_fma_f32 v38, -v38, v63, v62
	v_div_fmas_f32 v38, v38, v47, v63
	v_div_fixup_f32 v38, v38, v40, v43
	v_div_scale_f32 v43, s[34:35], v39, v39, 1.0
	v_rcp_f32_e32 v47, v43
	v_cndmask_b32_e64 v55, v246, v105, s[40:41]
	v_cndmask_b32_e64 v54, v247, v106, s[40:41]
	v_cndmask_b32_e64 v61, v107, v248, s[40:41]
	v_fma_f32 v62, -v43, v47, 1.0
	v_fmac_f32_e32 v47, v62, v47
	v_div_scale_f32 v62, vcc, 1.0, v39, 1.0
	v_mul_f32_e32 v63, v62, v47
	v_fma_f32 v64, -v43, v63, v62
	v_fmac_f32_e32 v63, v64, v47
	v_fma_f32 v43, -v43, v63, v62
	v_div_fmas_f32 v43, v43, v47, v63
	v_div_fixup_f32 v39, v43, v39, 1.0
	v_div_scale_f32 v43, s[34:35], v40, v40, v45
	v_rcp_f32_e32 v47, v43
	v_cndmask_b32_e64 v60, v108, v249, s[40:41]
	v_cndmask_b32_e64 v59, v250, v107, s[40:41]
	v_cndmask_b32_e64 v58, v251, v108, s[40:41]
	v_fma_f32 v62, -v43, v47, 1.0
	v_fmac_f32_e32 v47, v62, v47
	v_div_scale_f32 v62, vcc, v45, v40, v45
	v_mul_f32_e32 v63, v62, v47
	v_fma_f32 v64, -v43, v63, v62
	v_fmac_f32_e32 v63, v64, v47
	v_fma_f32 v43, -v43, v63, v62
	v_div_fmas_f32 v43, v43, v47, v63
	v_div_fixup_f32 v47, v43, v40, v45
	v_pk_mul_f32 v[46:47], v[38:39], v[46:47]
	v_mov_b32_e32 v39, v18
	v_mov_b32_e32 v43, v47
	v_pk_mul_f32 v[42:43], v[38:39], v[42:43]
	v_mov_b32_e32 v39, v19
	v_mov_b32_e32 v45, v47
	v_pk_mul_f32 v[18:19], v[38:39], v[44:45]
	v_fma_f32 v20, v20, v47, v46
	v_and_b32_e32 v46, 0xffff0000, v49
	v_mov_b32_e32 v39, v21
	v_add_f32_e32 v42, v42, v43
	v_add_f32_e32 v43, v18, v19
	v_pk_mul_f32 v[18:19], v[38:39], v[46:47]
	v_lshlrev_b32_e32 v46, 16, v48
	v_add_f32_e32 v18, v18, v19
	v_mov_b32_e32 v39, v22
	v_cvt_pk_bf16_f32 v21, v42, v43
	v_cvt_pk_bf16_f32 v20, v20, v18
	v_pk_mul_f32 v[18:19], v[38:39], v[46:47]
	v_and_b32_e32 v46, 0xffff0000, v48
	v_mov_b32_e32 v39, v23
	v_add_f32_e32 v22, v18, v19
	v_pk_mul_f32 v[18:19], v[38:39], v[46:47]
	v_lshlrev_b32_e32 v46, 16, v41
	v_mov_b32_e32 v39, v24
	v_add_f32_e32 v23, v18, v19
	v_pk_mul_f32 v[18:19], v[38:39], v[46:47]
	v_and_b32_e32 v46, 0xffff0000, v41
	v_mov_b32_e32 v39, v25
	v_add_f32_e32 v24, v18, v19
	v_pk_mul_f32 v[18:19], v[38:39], v[46:47]
	v_lshlrev_b32_e32 v46, 16, v53
	v_add_f32_e32 v18, v18, v19
	v_mov_b32_e32 v39, v26
	v_cvt_pk_bf16_f32 v22, v22, v23
	v_cvt_pk_bf16_f32 v23, v24, v18
	v_pk_mul_f32 v[18:19], v[38:39], v[46:47]
	v_and_b32_e32 v46, 0xffff0000, v53
	v_mov_b32_e32 v39, v27
	v_add_f32_e32 v24, v18, v19
	v_pk_mul_f32 v[18:19], v[38:39], v[46:47]
	v_lshlrev_b32_e32 v46, 16, v52
	v_mov_b32_e32 v39, v28
	v_add_f32_e32 v25, v18, v19
	v_pk_mul_f32 v[18:19], v[38:39], v[46:47]
	v_and_b32_e32 v46, 0xffff0000, v52
	v_mov_b32_e32 v39, v29
	v_add_f32_e32 v26, v18, v19
	v_pk_mul_f32 v[18:19], v[38:39], v[46:47]
	v_lshlrev_b32_e32 v46, 16, v51
	v_add_f32_e32 v18, v18, v19
	v_mov_b32_e32 v39, v30
	v_cvt_pk_bf16_f32 v24, v24, v25
	v_cvt_pk_bf16_f32 v25, v26, v18
	v_pk_mul_f32 v[18:19], v[38:39], v[46:47]
	v_and_b32_e32 v46, 0xffff0000, v51
	v_mov_b32_e32 v39, v31
	v_add_f32_e32 v26, v18, v19
	v_pk_mul_f32 v[18:19], v[38:39], v[46:47]
	v_lshlrev_b32_e32 v46, 16, v50
	v_mov_b32_e32 v39, v32
	v_add_f32_e32 v27, v18, v19
	v_pk_mul_f32 v[18:19], v[38:39], v[46:47]
	v_and_b32_e32 v46, 0xffff0000, v50
	v_mov_b32_e32 v39, v33
	v_add_f32_e32 v28, v18, v19
; __device__ __forceinline__ unsigned cvt_pk_bf16(float lo, float hi) { unsigned r; asm volatile("v_cvt_pk_bf16_f32 %0, %1, %2" : "=v"(r) : "v"(lo), "v"(hi)); return r; }
; template <int P_>
; __device__ __forceinline__ void dil_wave_unit(LAS unsigned char* wl, const bf16_t* DIL, bf16_t* Y, bf16_t* ST, float* LSE, const float* BT, int b, int h, int r, int nb) {
;     ...
;         for (int e = 0; e < 8; ++e) { const int blk = e >> 2, g = e & 3;
;             float v0 = o[qh][blk][4 * g] * a_cur, v1 = o[qh][blk][4 * g + 1] * a_cur, v2 = o[qh][blk][4 * g + 2] * a_cur, v3 = o[qh][blk][4 * g + 3] * a_cur;
;             if (!first) { v0 += a_prev * bf_lo(pv[qh][e].x); v1 += a_prev * bf_hi(pv[qh][e].x); v2 += a_prev * bf_lo(pv[qh][e].y); v3 += a_prev * bf_hi(pv[qh][e].y); }
;             wv[e].x = cvt_pk_bf16(v0, v1); wv[e].y = cvt_pk_bf16(v2, v3); }
; #pragma unroll
;         for (int e = 0; e < 8; e += 2) { const u32x2 snd = hi ? wv[e] : wv[e + 1]; u32x2 rcv; rcv.x = __shfl_xor(snd.x, 32); rcv.y = __shfl_xor(snd.y, 32);
;             u32x4 o4; if (hi) { o4.x = rcv.x; o4.y = rcv.y; o4.z = wv[e + 1].x; o4.w = wv[e + 1].y; } else { o4.x = wv[e].x; o4.y = wv[e].y; o4.z = rcv.x; o4.w = rcv.y; }
;             *(u32x4*)(ypb + 32 * (e >> 2) + 8 * ((e & 3) + hi)) = o4; }
;         if (!last && hi == 0) LSE[srow] = lse_new;
	v_pk_mul_f32 v[18:19], v[38:39], v[46:47]
	v_lshlrev_b32_e32 v46, 16, v57
	v_add_f32_e32 v18, v18, v19
	v_mov_b32_e32 v39, v2
	v_cvt_pk_bf16_f32 v26, v26, v27
	v_cvt_pk_bf16_f32 v27, v28, v18
	v_pk_mul_f32 v[18:19], v[38:39], v[46:47]
	v_and_b32_e32 v46, 0xffff0000, v57
	v_mov_b32_e32 v39, v3
	v_pk_mul_f32 v[2:3], v[38:39], v[46:47]
	v_lshlrev_b32_e32 v46, 16, v56
	v_mov_b32_e32 v39, v4
	v_add_f32_e32 v18, v18, v19
	v_add_f32_e32 v19, v2, v3
	v_pk_mul_f32 v[2:3], v[38:39], v[46:47]
	v_and_b32_e32 v46, 0xffff0000, v56
	v_mov_b32_e32 v39, v5
	v_add_f32_e32 v4, v2, v3
	v_pk_mul_f32 v[2:3], v[38:39], v[46:47]
	v_lshlrev_b32_e32 v46, 16, v55
	v_add_f32_e32 v2, v2, v3
	v_mov_b32_e32 v39, v6
	v_cvt_pk_bf16_f32 v18, v18, v19
	v_cvt_pk_bf16_f32 v19, v4, v2
	v_pk_mul_f32 v[2:3], v[38:39], v[46:47]
	v_and_b32_e32 v46, 0xffff0000, v55
	v_mov_b32_e32 v39, v7
	v_add_f32_e32 v4, v2, v3
	v_pk_mul_f32 v[2:3], v[38:39], v[46:47]
	v_lshlrev_b32_e32 v46, 16, v54
	v_mov_b32_e32 v39, v8
	v_add_f32_e32 v5, v2, v3
	v_pk_mul_f32 v[2:3], v[38:39], v[46:47]
	v_and_b32_e32 v46, 0xffff0000, v54
	v_mov_b32_e32 v39, v9
	v_add_f32_e32 v6, v2, v3
	v_pk_mul_f32 v[2:3], v[38:39], v[46:47]
	v_lshlrev_b32_e32 v46, 16, v61
	v_add_f32_e32 v2, v2, v3
	v_mov_b32_e32 v39, v10
	v_cvt_pk_bf16_f32 v8, v4, v5
	v_cvt_pk_bf16_f32 v9, v6, v2
	v_pk_mul_f32 v[2:3], v[38:39], v[46:47]
	v_and_b32_e32 v46, 0xffff0000, v61
	v_mov_b32_e32 v39, v11
	v_add_f32_e32 v4, v2, v3
	v_pk_mul_f32 v[2:3], v[38:39], v[46:47]
	v_lshlrev_b32_e32 v46, 16, v60
	v_mov_b32_e32 v39, v12
	v_add_f32_e32 v5, v2, v3
	v_pk_mul_f32 v[2:3], v[38:39], v[46:47]
	v_and_b32_e32 v46, 0xffff0000, v60
	v_mov_b32_e32 v39, v13
	v_add_f32_e32 v6, v2, v3
	v_pk_mul_f32 v[2:3], v[38:39], v[46:47]
	v_lshlrev_b32_e32 v46, 16, v59
	v_add_f32_e32 v2, v2, v3
	v_mov_b32_e32 v39, v14
	v_cvt_pk_bf16_f32 v10, v4, v5
	v_cvt_pk_bf16_f32 v11, v6, v2
	v_pk_mul_f32 v[2:3], v[38:39], v[46:47]
	v_and_b32_e32 v46, 0xffff0000, v59
	v_mov_b32_e32 v39, v15
	v_add_f32_e32 v4, v2, v3
	v_pk_mul_f32 v[2:3], v[38:39], v[46:47]
	v_lshlrev_b32_e32 v46, 16, v58
	v_mov_b32_e32 v39, v16
	v_add_f32_e32 v5, v2, v3
	v_pk_mul_f32 v[2:3], v[38:39], v[46:47]
	v_and_b32_e32 v46, 0xffff0000, v58
	v_mov_b32_e32 v39, v17
	v_add_f32_e32 v6, v2, v3
	v_pk_mul_f32 v[2:3], v[38:39], v[46:47]
	v_cvt_pk_bf16_f32 v12, v4, v5
	v_cndmask_b32_e64 v15, v25, v27, s[40:41]
	v_add_f32_e32 v2, v2, v3
	v_cvt_pk_bf16_f32 v13, v6, v2
	v_cndmask_b32_e64 v2, v20, v23, s[40:41]
	v_cndmask_b32_e64 v3, v21, v22, s[40:41]
	ds_bpermute_b32 v3, v208, v3
	ds_bpermute_b32 v14, v208, v2
	v_cndmask_b32_e64 v16, v24, v26, s[40:41]
	v_mov_b32_e32 v87, v1
	v_lshl_add_u64 v[34:35], s[8:9], 0, v[86:87]
	s_waitcnt lgkmcnt(1)
	v_cndmask_b32_e64 v4, v22, v3, s[40:41]
	v_cndmask_b32_e64 v2, v3, v21, s[40:41]
	s_waitcnt lgkmcnt(0)
	v_cndmask_b32_e64 v5, v23, v14, s[40:41]
	v_cndmask_b32_e64 v3, v14, v20, s[40:41]
	global_store_dwordx4 v[82:83], v[2:5], off
	ds_bpermute_b32 v2, v208, v16
	ds_bpermute_b32 v3, v208, v15
	v_lshlrev_b64 v[36:37], 7, v[34:35]
	v_lshl_add_u64 v[6:7], s[12:13], 0, v[36:37]
	v_cndmask_b32_e64 v14, v19, v9, s[40:41]
	v_cndmask_b32_e64 v15, v18, v8, s[40:41]
	s_waitcnt lgkmcnt(1)
	v_cndmask_b32_e64 v4, v26, v2, s[40:41]
	v_cndmask_b32_e64 v2, v2, v24, s[40:41]
	s_waitcnt lgkmcnt(0)
	v_cndmask_b32_e64 v5, v27, v3, s[40:41]
	v_cndmask_b32_e64 v3, v3, v25, s[40:41]
	v_lshl_add_u64 v[6:7], v[6:7], 0, v[156:157]
	global_store_dwordx4 v[6:7], v[2:5], off offset:32
	ds_bpermute_b32 v2, v208, v15
	ds_bpermute_b32 v3, v208, v14
	v_cndmask_b32_e64 v14, v11, v13, s[40:41]
	v_cndmask_b32_e64 v15, v10, v12, s[40:41]
	s_waitcnt lgkmcnt(1)
	v_cndmask_b32_e64 v4, v8, v2, s[40:41]
	v_cndmask_b32_e64 v2, v2, v18, s[40:41]
	s_waitcnt lgkmcnt(0)
	v_cndmask_b32_e64 v5, v9, v3, s[40:41]
	v_cndmask_b32_e64 v3, v3, v19, s[40:41]
	global_store_dwordx4 v[82:83], v[2:5], off offset:64
	ds_bpermute_b32 v2, v208, v15
	ds_bpermute_b32 v3, v208, v14
	s_waitcnt lgkmcnt(1)
	v_cndmask_b32_e64 v4, v12, v2, s[40:41]
	v_cndmask_b32_e64 v2, v2, v10, s[40:41]
	s_waitcnt lgkmcnt(0)
	v_cndmask_b32_e64 v5, v13, v3, s[40:41]
	v_cndmask_b32_e64 v3, v3, v11, s[40:41]
	global_store_dwordx4 v[6:7], v[2:5], off offset:96
	s_and_saveexec_b64 s[34:35], s[40:41]
	s_cbranch_execz .LBB0_447
	v_log_f32_e32 v2, v40
	s_nop 0
	v_add_f32_e32 v0, v0, v2
	v_lshl_add_u64 v[2:3], v[34:35], 2, s[14:15]
	global_store_dword v[2:3], v0, off
	s_branch .LBB0_447

; template <int P_>
; __device__ __forceinline__ void dil_wave_unit(LAS unsigned char* wl, const bf16_t* DIL, bf16_t* Y, bf16_t* ST, float* LSE, const float* BT, int b, int h, int r, int nb) {
;     ...
;         for (int qh = 0; qh < 2; ++qh) { const size_t srow = (size_t)(b * 8 + h) * SEQ + (size_t)(64 * nb + 32 * qh + r32) * dil + r; lp[qh] = LSE[srow];
;             const bf16_t* spb = ST + srow * 64;
; #pragma unroll
;             for (int e = 0; e < 8; e += 2) { const u32x4 L = *(const u32x4*)(spb + 32 * (e >> 2) + 8 * ((e & 3) + hi));
;                 u32x2 snd; snd.x = hi ? L.x : L.z; snd.y = hi ? L.y : L.w; u32x2 rcv; rcv.x = __shfl_xor(snd.x, 32); rcv.y = __shfl_xor(snd.y, 32);
;                 if (hi) { pv[qh][e] = rcv; pv[qh][e + 1].x = L.z; pv[qh][e + 1].y = L.w; } else { pv[qh][e].x = L.x; pv[qh][e].y = L.y; pv[qh][e + 1] = rcv; } } }
.LBB0_462:
	v_lshl_or_b32 v0, v210, 4, s37
	v_or_b32_e32 v72, s18, v0
	v_mov_b32_e32 v73, s19
	v_lshl_add_u64 v[66:67], v[72:73], 0, s[34:35]
	v_lshl_add_u64 v[68:69], v[66:67], 2, s[14:15]
	v_lshlrev_b64 v[66:67], 7, v[66:67]
	v_lshl_add_u64 v[66:67], s[12:13], 0, v[66:67]
	v_mov_b32_e32 v157, v1
	v_lshl_add_u64 v[74:75], v[66:67], 0, v[156:157]
	global_load_dword v71, v[68:69], off
	v_cmp_gt_u32_e64 s[40:41], 32, v209
	global_load_dwordx4 v[66:69], v[74:75], off
	global_load_dwordx4 v[240:243], v[74:75], off offset:32
	global_load_dwordx4 v[244:247], v[74:75], off offset:64
	global_load_dwordx4 v[248:251], v[74:75], off offset:96
	s_xor_b64 s[42:43], s[38:39], -1
	s_mov_b32 s44, 1
	s_waitcnt vmcnt(0)
	v_cndmask_b32_e64 v70, v66, v68, s[40:41]
	v_cndmask_b32_e64 v72, v67, v69, s[40:41]
	ds_bpermute_b32 v70, v208, v70
	ds_bpermute_b32 v72, v208, v72
	s_waitcnt lgkmcnt(1)
	v_cndmask_b32_e64 v107, v68, v70, s[40:41]
	s_waitcnt lgkmcnt(0)
	v_cndmask_b32_e64 v104, v69, v72, s[40:41]
	v_cndmask_b32_e64 v109, v72, v67, s[40:41]
	v_cndmask_b32_e64 v70, v70, v66, s[40:41]
	s_waitcnt vmcnt(0)
	v_cndmask_b32_e64 v72, v240, v242, s[40:41]
	v_cndmask_b32_e64 v76, v241, v243, s[40:41]
	ds_bpermute_b32 v72, v208, v72
	ds_bpermute_b32 v76, v208, v76
	s_waitcnt lgkmcnt(1)
	v_cndmask_b32_e64 v103, v242, v72, s[40:41]
	s_waitcnt lgkmcnt(0)
	v_cndmask_b32_e64 v100, v243, v76, s[40:41]
	v_cndmask_b32_e64 v106, v76, v241, s[40:41]
	v_cndmask_b32_e64 v108, v72, v240, s[40:41]
	s_waitcnt vmcnt(0)
	v_cndmask_b32_e64 v72, v244, v246, s[40:41]
	v_cndmask_b32_e64 v76, v245, v247, s[40:41]
	ds_bpermute_b32 v72, v208, v72
	ds_bpermute_b32 v76, v208, v76
	s_waitcnt lgkmcnt(1)
	v_cndmask_b32_e64 v99, v246, v72, s[40:41]
	s_waitcnt lgkmcnt(0)
	v_cndmask_b32_e64 v97, v247, v76, s[40:41]
	v_cndmask_b32_e64 v102, v76, v245, s[40:41]
	v_cndmask_b32_e64 v105, v72, v244, s[40:41]
	s_waitcnt vmcnt(0)
	v_cndmask_b32_e64 v72, v248, v250, s[40:41]
	ds_bpermute_b32 v72, v208, v72
	v_cndmask_b32_e64 v74, v249, v251, s[40:41]
	ds_bpermute_b32 v74, v208, v74
	s_waitcnt lgkmcnt(1)
	v_cndmask_b32_e64 v101, v72, v248, s[40:41]
	v_or_b32_e32 v66, 0x200, v0
	v_cndmask_b32_e64 v96, v250, v72, s[40:41]
	v_or_b32_e32 v72, s18, v66
	s_waitcnt lgkmcnt(0)
	v_cndmask_b32_e64 v95, v251, v74, s[40:41]
	v_lshl_add_u64 v[68:69], v[72:73], 0, s[34:35]
	v_lshl_add_u64 v[72:73], v[68:69], 2, s[14:15]
	v_lshlrev_b64 v[68:69], 7, v[68:69]
	v_lshl_add_u64 v[68:69], s[12:13], 0, v[68:69]
	v_lshl_add_u64 v[68:69], v[68:69], 0, v[156:157]
	v_cndmask_b32_e64 v98, v74, v249, s[40:41]
	global_load_dword v93, v[72:73], off
	v_mov_b32_e32 v67, v1
	global_load_dwordx4 v[72:75], v[68:69], off
	global_load_dwordx4 v[240:243], v[68:69], off offset:32
	global_load_dwordx4 v[244:247], v[68:69], off offset:64
	global_load_dwordx4 v[248:251], v[68:69], off offset:96
	s_waitcnt vmcnt(0)
	v_cndmask_b32_e64 v76, v72, v74, s[40:41]
	v_cndmask_b32_e64 v77, v73, v75, s[40:41]
	ds_bpermute_b32 v76, v208, v76
	ds_bpermute_b32 v77, v208, v77
	s_waitcnt lgkmcnt(1)
	v_cndmask_b32_e64 v90, v74, v76, s[40:41]
	s_waitcnt lgkmcnt(0)
	v_cndmask_b32_e64 v87, v75, v77, s[40:41]
	v_cndmask_b32_e64 v92, v77, v73, s[40:41]
	v_cndmask_b32_e64 v94, v76, v72, s[40:41]
	s_waitcnt vmcnt(0)
	v_cndmask_b32_e64 v76, v240, v242, s[40:41]
	v_cndmask_b32_e64 v77, v241, v243, s[40:41]
	ds_bpermute_b32 v76, v208, v76
	ds_bpermute_b32 v77, v208, v77
	s_waitcnt lgkmcnt(1)
	v_cndmask_b32_e64 v86, v242, v76, s[40:41]
	s_waitcnt lgkmcnt(0)
	v_cndmask_b32_e64 v83, v243, v77, s[40:41]
	v_cndmask_b32_e64 v89, v77, v241, s[40:41]
	v_cndmask_b32_e64 v91, v76, v240, s[40:41]
	s_waitcnt vmcnt(0)
	v_cndmask_b32_e64 v76, v244, v246, s[40:41]
	v_cndmask_b32_e64 v77, v245, v247, s[40:41]
	ds_bpermute_b32 v76, v208, v76
	ds_bpermute_b32 v77, v208, v77
	s_waitcnt lgkmcnt(1)
	v_cndmask_b32_e64 v82, v246, v76, s[40:41]
	s_waitcnt lgkmcnt(0)
	v_cndmask_b32_e64 v80, v247, v77, s[40:41]
	v_cndmask_b32_e64 v85, v77, v245, s[40:41]
	v_cndmask_b32_e64 v88, v76, v244, s[40:41]
	s_waitcnt vmcnt(0)
	v_cndmask_b32_e64 v68, v248, v250, s[40:41]
	v_cndmask_b32_e64 v69, v249, v251, s[40:41]
	ds_bpermute_b32 v68, v208, v68
	ds_bpermute_b32 v69, v208, v69
	s_waitcnt lgkmcnt(1)
	v_cndmask_b32_e64 v79, v250, v68, s[40:41]
	s_waitcnt lgkmcnt(0)
	v_cndmask_b32_e64 v78, v251, v69, s[40:41]
	v_cndmask_b32_e64 v81, v69, v249, s[40:41]
	v_cndmask_b32_e64 v84, v68, v248, s[40:41]
	v_lshl_add_u64 v[68:69], v[0:1], 0, s[34:35]
	ds_bpermute_b32 v0, v208, v155
	v_max_f32_e32 v75, v71, v71
	v_lshlrev_b32_e32 v74, 16, v109
	v_lshlrev_b32_e32 v72, 16, v70
	v_and_b32_e32 v70, 0xffff0000, v70
	s_waitcnt lgkmcnt(0)
; __device__ __forceinline__ unsigned cvt_pk_bf16(float lo, float hi) { unsigned r; asm volatile("v_cvt_pk_bf16_f32 %0, %1, %2" : "=v"(r) : "v"(lo), "v"(hi)); return r; }
; template <int P_>
; __device__ __forceinline__ void dil_wave_unit(LAS unsigned char* wl, const bf16_t* DIL, bf16_t* Y, bf16_t* ST, float* LSE, const float* BT, int b, int h, int r, int nb) {
;     ...
;         const size_t spos = (size_t)(64 * nb + 32 * qh + r32) * dil + r; const size_t srow = (size_t)(b * 8 + h) * SEQ + spos;
;         const float lt = l_run[qh] + __shfl_xor(l_run[qh], 32); const float inv = 1.0f / lt; const float lse2 = m_run[qh] + __builtin_amdgcn_logf(lt);
;         float a_prev = 0.f, a_cur = inv, lse_new = lse2;
;         if (!first) { const float M = fmaxf(lp[qh], lse2); const float wp = __builtin_amdgcn_exp2f(lp[qh] - M), wc = __builtin_amdgcn_exp2f(lse2 - M); const float den = wp + wc;
;             a_prev = wp / den; a_cur = wc / den * inv; lse_new = M + __builtin_amdgcn_logf(den); }
;         bf16_t* ypb = last ? Y + (tok0 + spos) * 1024 + 512 + h * 64 : ST + srow * 64;
;         u32x2 wv[8];
; #pragma unroll
;         for (int e = 0; e < 8; ++e) { const int blk = e >> 2, g = e & 3;
;             float v0 = o[qh][blk][4 * g] * a_cur, v1 = o[qh][blk][4 * g + 1] * a_cur, v2 = o[qh][blk][4 * g + 2] * a_cur, v3 = o[qh][blk][4 * g + 3] * a_cur;
;             if (!first) { v0 += a_prev * bf_lo(pv[qh][e].x); v1 += a_prev * bf_hi(pv[qh][e].x); v2 += a_prev * bf_lo(pv[qh][e].y); v3 += a_prev * bf_hi(pv[qh][e].y); }
;             wv[e].x = cvt_pk_bf16(v0, v1); wv[e].y = cvt_pk_bf16(v2, v3); }
	v_add_f32_e32 v0, v155, v0
	v_log_f32_e32 v73, v0
	v_lshlrev_b64 v[68:69], 11, v[68:69]
	v_add_f32_e32 v73, v233, v73
	v_max_f32_e32 v75, v75, v73
	v_sub_f32_e32 v71, v71, v75
	v_sub_f32_e32 v73, v73, v75
	v_exp_f32_e32 v71, v71
	v_exp_f32_e32 v73, v73
	s_nop 0
	v_add_f32_e32 v75, v71, v73
	v_div_scale_f32 v76, s[38:39], v75, v75, v71
	v_rcp_f32_e32 v77, v76
	s_nop 0
	v_fma_f32 v110, -v76, v77, 1.0
	v_fmac_f32_e32 v77, v110, v77
	v_div_scale_f32 v110, vcc, v71, v75, v71
	v_mul_f32_e32 v111, v110, v77
	v_fma_f32 v112, -v76, v111, v110
	v_fmac_f32_e32 v111, v112, v77
	v_fma_f32 v76, -v76, v111, v110
	v_div_fmas_f32 v76, v76, v77, v111
	v_div_fixup_f32 v76, v76, v75, v71
	v_div_scale_f32 v71, s[38:39], v0, v0, 1.0
	v_rcp_f32_e32 v77, v71
	s_nop 0
	v_fma_f32 v110, -v71, v77, 1.0
	v_fmac_f32_e32 v77, v110, v77
	v_div_scale_f32 v110, vcc, 1.0, v0, 1.0
	v_mul_f32_e32 v111, v110, v77
	v_fma_f32 v112, -v71, v111, v110
	v_fmac_f32_e32 v111, v112, v77
	v_fma_f32 v71, -v71, v111, v110
	v_div_fmas_f32 v71, v71, v77, v111
	v_div_fixup_f32 v77, v71, v0, 1.0
	v_div_scale_f32 v0, s[38:39], v75, v75, v73
	v_rcp_f32_e32 v71, v0
	s_mov_b64 s[38:39], 0
	v_fma_f32 v110, -v0, v71, 1.0
	v_fmac_f32_e32 v71, v110, v71
	v_div_scale_f32 v110, vcc, v73, v75, v73
	v_mul_f32_e32 v111, v110, v71
	v_fma_f32 v112, -v0, v111, v110
	v_fmac_f32_e32 v111, v112, v71
	v_fma_f32 v0, -v0, v111, v110
	v_div_fmas_f32 v0, v0, v71, v111
	v_div_fixup_f32 v75, v0, v75, v73
	v_pk_mul_f32 v[74:75], v[76:77], v[74:75]
	v_mov_b32_e32 v77, v50
	v_mov_b32_e32 v73, v75
	v_pk_mul_f32 v[72:73], v[76:77], v[72:73]
	v_mov_b32_e32 v77, v51
	v_mov_b32_e32 v71, v75
	v_pk_mul_f32 v[50:51], v[76:77], v[70:71]
	v_fma_f32 v52, v52, v75, v74
	v_and_b32_e32 v74, 0xffff0000, v109
	v_mov_b32_e32 v77, v53
	v_add_f32_e32 v70, v50, v51
	v_pk_mul_f32 v[50:51], v[76:77], v[74:75]
	v_add_f32_e32 v0, v72, v73
	v_add_f32_e32 v50, v50, v51
	v_lshlrev_b32_e32 v74, 16, v107
	v_mov_b32_e32 v77, v54
	v_cvt_pk_bf16_f32 v0, v0, v70
	v_cvt_pk_bf16_f32 v52, v52, v50
	v_pk_mul_f32 v[50:51], v[76:77], v[74:75]
	v_and_b32_e32 v74, 0xffff0000, v107
	v_mov_b32_e32 v77, v55
	v_add_f32_e32 v53, v50, v51
	v_pk_mul_f32 v[50:51], v[76:77], v[74:75]
	v_lshlrev_b32_e32 v74, 16, v104
	v_mov_b32_e32 v77, v56
	v_add_f32_e32 v54, v50, v51
	v_pk_mul_f32 v[50:51], v[76:77], v[74:75]
	v_and_b32_e32 v74, 0xffff0000, v104
	v_mov_b32_e32 v77, v57
	v_add_f32_e32 v55, v50, v51
	v_pk_mul_f32 v[50:51], v[76:77], v[74:75]
	v_lshlrev_b32_e32 v74, 16, v108
	v_add_f32_e32 v50, v50, v51
	v_mov_b32_e32 v77, v58
	v_cvt_pk_bf16_f32 v53, v53, v54
	v_cvt_pk_bf16_f32 v54, v55, v50
	v_pk_mul_f32 v[50:51], v[76:77], v[74:75]
	v_and_b32_e32 v74, 0xffff0000, v108
	v_mov_b32_e32 v77, v59
	v_add_f32_e32 v55, v50, v51
	v_pk_mul_f32 v[50:51], v[76:77], v[74:75]
	v_lshlrev_b32_e32 v74, 16, v106
	v_mov_b32_e32 v77, v60
	v_add_f32_e32 v56, v50, v51
	v_pk_mul_f32 v[50:51], v[76:77], v[74:75]
	v_and_b32_e32 v74, 0xffff0000, v106
	v_mov_b32_e32 v77, v61
	v_add_f32_e32 v57, v50, v51
	v_pk_mul_f32 v[50:51], v[76:77], v[74:75]
	v_lshlrev_b32_e32 v74, 16, v103
	v_add_f32_e32 v50, v50, v51
	v_mov_b32_e32 v77, v62
	v_cvt_pk_bf16_f32 v55, v55, v56
	v_cvt_pk_bf16_f32 v56, v57, v50
	v_pk_mul_f32 v[50:51], v[76:77], v[74:75]
	v_and_b32_e32 v74, 0xffff0000, v103
	v_mov_b32_e32 v77, v63
	v_add_f32_e32 v57, v50, v51
	v_pk_mul_f32 v[50:51], v[76:77], v[74:75]
	v_lshlrev_b32_e32 v74, 16, v100
	v_mov_b32_e32 v77, v64
	v_add_f32_e32 v58, v50, v51
	v_pk_mul_f32 v[50:51], v[76:77], v[74:75]
	v_and_b32_e32 v74, 0xffff0000, v100
	v_mov_b32_e32 v77, v65
	v_add_f32_e32 v59, v50, v51
	v_pk_mul_f32 v[50:51], v[76:77], v[74:75]
	v_lshlrev_b32_e32 v74, 16, v105
	v_add_f32_e32 v50, v50, v51
	v_mov_b32_e32 v77, v34
	v_cvt_pk_bf16_f32 v57, v57, v58
	v_cvt_pk_bf16_f32 v58, v59, v50
	v_pk_mul_f32 v[50:51], v[76:77], v[74:75]
	v_and_b32_e32 v74, 0xffff0000, v105
	v_mov_b32_e32 v77, v35
	v_pk_mul_f32 v[34:35], v[76:77], v[74:75]
	v_lshlrev_b32_e32 v74, 16, v102
	v_mov_b32_e32 v77, v36
	v_add_f32_e32 v50, v50, v51
	v_add_f32_e32 v51, v34, v35
	v_pk_mul_f32 v[34:35], v[76:77], v[74:75]
	v_and_b32_e32 v74, 0xffff0000, v102
	v_mov_b32_e32 v77, v37
	v_add_f32_e32 v36, v34, v35
	v_pk_mul_f32 v[34:35], v[76:77], v[74:75]
	v_lshlrev_b32_e32 v74, 16, v99
	v_add_f32_e32 v34, v34, v35
	v_mov_b32_e32 v77, v38
	v_cvt_pk_bf16_f32 v50, v50, v51
	v_cvt_pk_bf16_f32 v51, v36, v34
	v_pk_mul_f32 v[34:35], v[76:77], v[74:75]
	v_and_b32_e32 v74, 0xffff0000, v99
	v_mov_b32_e32 v77, v39
	v_add_f32_e32 v36, v34, v35
	v_pk_mul_f32 v[34:35], v[76:77], v[74:75]
	v_lshlrev_b32_e32 v74, 16, v97
	v_mov_b32_e32 v77, v40
	v_add_f32_e32 v37, v34, v35
	v_pk_mul_f32 v[34:35], v[76:77], v[74:75]
	v_and_b32_e32 v74, 0xffff0000, v97
	v_mov_b32_e32 v77, v41
	v_add_f32_e32 v38, v34, v35
	v_pk_mul_f32 v[34:35], v[76:77], v[74:75]
	v_lshlrev_b32_e32 v74, 16, v101
	v_add_f32_e32 v34, v34, v35
	v_mov_b32_e32 v77, v42
	v_cvt_pk_bf16_f32 v40, v36, v37
	v_cvt_pk_bf16_f32 v41, v38, v34
	v_pk_mul_f32 v[34:35], v[76:77], v[74:75]
	v_and_b32_e32 v74, 0xffff0000, v101
	v_mov_b32_e32 v77, v43
	v_add_f32_e32 v36, v34, v35
	v_pk_mul_f32 v[34:35], v[76:77], v[74:75]
	v_lshlrev_b32_e32 v74, 16, v98
	v_mov_b32_e32 v77, v44
	v_add_f32_e32 v37, v34, v35
	v_pk_mul_f32 v[34:35], v[76:77], v[74:75]
	v_and_b32_e32 v74, 0xffff0000, v98
	v_mov_b32_e32 v77, v45
	v_add_f32_e32 v38, v34, v35
	v_pk_mul_f32 v[34:35], v[76:77], v[74:75]
	v_lshlrev_b32_e32 v74, 16, v96
	v_add_f32_e32 v34, v34, v35
	v_mov_b32_e32 v77, v46
	v_cvt_pk_bf16_f32 v42, v36, v37
	v_cvt_pk_bf16_f32 v43, v38, v34
	v_pk_mul_f32 v[34:35], v[76:77], v[74:75]
	v_and_b32_e32 v74, 0xffff0000, v96
	v_mov_b32_e32 v77, v47
	v_add_f32_e32 v36, v34, v35
	v_pk_mul_f32 v[34:35], v[76:77], v[74:75]
	v_lshlrev_b32_e32 v74, 16, v95
	v_mov_b32_e32 v77, v48
	v_add_f32_e32 v37, v34, v35
	v_pk_mul_f32 v[34:35], v[76:77], v[74:75]
	v_and_b32_e32 v74, 0xffff0000, v95
	v_mov_b32_e32 v77, v49
	v_add_f32_e32 v38, v34, v35
	v_pk_mul_f32 v[34:35], v[76:77], v[74:75]
	v_cvt_pk_bf16_f32 v44, v36, v37
	v_cndmask_b32_e64 v47, v55, v57, s[40:41]
	v_add_f32_e32 v34, v34, v35
	v_cvt_pk_bf16_f32 v45, v38, v34
	v_cndmask_b32_e64 v34, v0, v53, s[40:41]
	ds_bpermute_b32 v34, v208, v34
	v_cndmask_b32_e64 v35, v52, v54, s[40:41]
	ds_bpermute_b32 v35, v208, v35
	v_lshl_add_u64 v[38:39], s[8:9], 0, v[68:69]
	v_cndmask_b32_e64 v46, v56, v58, s[40:41]
	s_waitcnt lgkmcnt(1)
; __device__ __forceinline__ unsigned cvt_pk_bf16(float lo, float hi) { unsigned r; asm volatile("v_cvt_pk_bf16_f32 %0, %1, %2" : "=v"(r) : "v"(lo), "v"(hi)); return r; }
; template <int P_>
; __device__ __forceinline__ void dil_wave_unit(LAS unsigned char* wl, const bf16_t* DIL, bf16_t* Y, bf16_t* ST, float* LSE, const float* BT, int b, int h, int r, int nb) {
;     ...
;         const size_t spos = (size_t)(64 * nb + 32 * qh + r32) * dil + r; const size_t srow = (size_t)(b * 8 + h) * SEQ + spos;
;         const float lt = l_run[qh] + __shfl_xor(l_run[qh], 32); const float inv = 1.0f / lt; const float lse2 = m_run[qh] + __builtin_amdgcn_logf(lt);
;         float a_prev = 0.f, a_cur = inv, lse_new = lse2;
;         if (!first) { const float M = fmaxf(lp[qh], lse2); const float wp = __builtin_amdgcn_exp2f(lp[qh] - M), wc = __builtin_amdgcn_exp2f(lse2 - M); const float den = wp + wc;
;             a_prev = wp / den; a_cur = wc / den * inv; lse_new = M + __builtin_amdgcn_logf(den); }
;     ...
;         for (int e = 0; e < 8; ++e) { const int blk = e >> 2, g = e & 3;
;             float v0 = o[qh][blk][4 * g] * a_cur, v1 = o[qh][blk][4 * g + 1] * a_cur, v2 = o[qh][blk][4 * g + 2] * a_cur, v3 = o[qh][blk][4 * g + 3] * a_cur;
;             if (!first) { v0 += a_prev * bf_lo(pv[qh][e].x); v1 += a_prev * bf_hi(pv[qh][e].x); v2 += a_prev * bf_lo(pv[qh][e].y); v3 += a_prev * bf_hi(pv[qh][e].y); }
;             wv[e].x = cvt_pk_bf16(v0, v1); wv[e].y = cvt_pk_bf16(v2, v3); }
; #pragma unroll
;         for (int e = 0; e < 8; e += 2) { const u32x2 snd = hi ? wv[e] : wv[e + 1]; u32x2 rcv; rcv.x = __shfl_xor(snd.x, 32); rcv.y = __shfl_xor(snd.y, 32);
;             u32x4 o4; if (hi) { o4.x = rcv.x; o4.y = rcv.y; o4.z = wv[e + 1].x; o4.w = wv[e + 1].y; } else { o4.x = wv[e].x; o4.y = wv[e].y; o4.z = rcv.x; o4.w = rcv.y; }
;             *(u32x4*)(ypb + 32 * (e >> 2) + 8 * ((e & 3) + hi)) = o4; }
	v_cndmask_b32_e64 v36, v53, v34, s[40:41]
	v_cndmask_b32_e64 v34, v34, v0, s[40:41]
	ds_bpermute_b32 v0, v208, v47
	s_waitcnt lgkmcnt(1)
	v_cndmask_b32_e64 v37, v54, v35, s[40:41]
	v_cndmask_b32_e64 v35, v35, v52, s[40:41]
	v_lshl_add_u64 v[38:39], v[38:39], 0, v[156:157]
	global_store_dwordx4 v[38:39], v[34:37], off offset:1024
	ds_bpermute_b32 v35, v208, v46
	v_cndmask_b32_e64 v47, v50, v40, s[40:41]
	s_waitcnt lgkmcnt(1)
	v_cndmask_b32_e64 v36, v57, v0, s[40:41]
	v_cndmask_b32_e64 v34, v0, v55, s[40:41]
	ds_bpermute_b32 v0, v208, v47
	v_cndmask_b32_e64 v46, v51, v41, s[40:41]
	s_waitcnt lgkmcnt(1)
	v_cndmask_b32_e64 v37, v58, v35, s[40:41]
	v_cndmask_b32_e64 v35, v35, v56, s[40:41]
	global_store_dwordx4 v[38:39], v[34:37], off offset:1056
	ds_bpermute_b32 v35, v208, v46
	v_cndmask_b32_e64 v47, v42, v44, s[40:41]
	s_waitcnt lgkmcnt(1)
	v_cndmask_b32_e64 v36, v40, v0, s[40:41]
	v_cndmask_b32_e64 v34, v0, v50, s[40:41]
	ds_bpermute_b32 v0, v208, v47
	v_cndmask_b32_e64 v46, v43, v45, s[40:41]
	s_waitcnt lgkmcnt(1)
	v_cndmask_b32_e64 v37, v41, v35, s[40:41]
	v_cndmask_b32_e64 v35, v35, v51, s[40:41]
	global_store_dwordx4 v[38:39], v[34:37], off offset:1088
	ds_bpermute_b32 v35, v208, v46
	v_and_b32_e32 v40, 0xffff0000, v94
	s_waitcnt lgkmcnt(1)
	v_cndmask_b32_e64 v36, v44, v0, s[40:41]
	v_cndmask_b32_e64 v34, v0, v42, s[40:41]
	ds_bpermute_b32 v0, v208, v154
	s_waitcnt lgkmcnt(1)
	v_cndmask_b32_e64 v37, v45, v35, s[40:41]
	v_cndmask_b32_e64 v35, v35, v43, s[40:41]
	global_store_dwordx4 v[38:39], v[34:37], off offset:1120
	v_lshlrev_b32_e32 v42, 16, v92
	s_waitcnt lgkmcnt(0)
	v_add_f32_e32 v0, v154, v0
	v_log_f32_e32 v36, v0
	v_max_f32_e32 v37, v93, v93
	v_lshl_add_u64 v[34:35], v[66:67], 0, s[34:35]
	v_lshlrev_b32_e32 v38, 16, v94
	v_add_f32_e32 v36, v130, v36
	v_max_f32_e32 v37, v37, v36
	v_sub_f32_e32 v39, v93, v37
	v_sub_f32_e32 v36, v36, v37
	v_exp_f32_e32 v39, v39
	v_exp_f32_e32 v41, v36
	v_lshlrev_b64 v[34:35], 11, v[34:35]
	v_add_f32_e32 v43, v39, v41
	v_div_scale_f32 v36, s[34:35], v43, v43, v39
	v_rcp_f32_e32 v37, v36
	s_nop 0
	v_fma_f32 v44, -v36, v37, 1.0
	v_fmac_f32_e32 v37, v44, v37
	v_div_scale_f32 v44, vcc, v39, v43, v39
	v_mul_f32_e32 v45, v44, v37
	v_fma_f32 v46, -v36, v45, v44
	v_fmac_f32_e32 v45, v46, v37
	v_fma_f32 v36, -v36, v45, v44
	v_div_fmas_f32 v36, v36, v37, v45
	v_div_scale_f32 v37, s[34:35], v0, v0, 1.0
	v_div_fixup_f32 v36, v36, v43, v39
	v_rcp_f32_e32 v39, v37
	s_nop 0
	v_fma_f32 v44, -v37, v39, 1.0
	v_fmac_f32_e32 v39, v44, v39
	v_div_scale_f32 v44, vcc, 1.0, v0, 1.0
	v_mul_f32_e32 v45, v44, v39
	v_fma_f32 v46, -v37, v45, v44
	v_fmac_f32_e32 v45, v46, v39
	v_fma_f32 v37, -v37, v45, v44
	v_div_fmas_f32 v37, v37, v39, v45
	v_div_fixup_f32 v37, v37, v0, 1.0
	v_div_scale_f32 v0, s[34:35], v43, v43, v41
	v_rcp_f32_e32 v39, v0
	s_nop 0
	v_fma_f32 v44, -v0, v39, 1.0
	v_fmac_f32_e32 v39, v44, v39
	v_div_scale_f32 v44, vcc, v41, v43, v41
	v_mul_f32_e32 v45, v44, v39
	v_fma_f32 v46, -v0, v45, v44
	v_fmac_f32_e32 v45, v46, v39
	v_fma_f32 v0, -v0, v45, v44
	v_div_fmas_f32 v0, v0, v39, v45
	v_div_fixup_f32 v43, v0, v43, v41
	v_pk_mul_f32 v[42:43], v[36:37], v[42:43]
	v_mov_b32_e32 v37, v18
	v_mov_b32_e32 v39, v43
	v_pk_mul_f32 v[38:39], v[36:37], v[38:39]
	v_mov_b32_e32 v37, v19
	v_mov_b32_e32 v41, v43
	v_pk_mul_f32 v[18:19], v[36:37], v[40:41]
	v_fma_f32 v20, v20, v43, v42
	v_and_b32_e32 v42, 0xffff0000, v92
	v_mov_b32_e32 v37, v21
	v_add_f32_e32 v0, v38, v39
	v_add_f32_e32 v38, v18, v19
	v_pk_mul_f32 v[18:19], v[36:37], v[42:43]
	v_lshlrev_b32_e32 v42, 16, v90
	v_add_f32_e32 v18, v18, v19
	v_mov_b32_e32 v37, v22
	v_cvt_pk_bf16_f32 v0, v0, v38
	v_cvt_pk_bf16_f32 v20, v20, v18
	v_pk_mul_f32 v[18:19], v[36:37], v[42:43]
	v_and_b32_e32 v42, 0xffff0000, v90
	v_mov_b32_e32 v37, v23
	v_add_f32_e32 v21, v18, v19
	v_pk_mul_f32 v[18:19], v[36:37], v[42:43]
	v_lshlrev_b32_e32 v42, 16, v87
	v_mov_b32_e32 v37, v24
	v_add_f32_e32 v22, v18, v19
	v_pk_mul_f32 v[18:19], v[36:37], v[42:43]
	v_and_b32_e32 v42, 0xffff0000, v87
	v_mov_b32_e32 v37, v25
	v_add_f32_e32 v23, v18, v19
	v_pk_mul_f32 v[18:19], v[36:37], v[42:43]
	v_lshlrev_b32_e32 v42, 16, v91
	v_add_f32_e32 v18, v18, v19
	v_mov_b32_e32 v37, v26
	v_cvt_pk_bf16_f32 v21, v21, v22
	v_cvt_pk_bf16_f32 v22, v23, v18
	v_pk_mul_f32 v[18:19], v[36:37], v[42:43]
	v_and_b32_e32 v42, 0xffff0000, v91
	v_mov_b32_e32 v37, v27
	v_add_f32_e32 v23, v18, v19
	v_pk_mul_f32 v[18:19], v[36:37], v[42:43]
	v_lshlrev_b32_e32 v42, 16, v89
	v_mov_b32_e32 v37, v28
	v_add_f32_e32 v24, v18, v19
	v_pk_mul_f32 v[18:19], v[36:37], v[42:43]
	v_and_b32_e32 v42, 0xffff0000, v89
	v_mov_b32_e32 v37, v29
	v_add_f32_e32 v25, v18, v19
	v_pk_mul_f32 v[18:19], v[36:37], v[42:43]
; __device__ __forceinline__ unsigned cvt_pk_bf16(float lo, float hi) { unsigned r; asm volatile("v_cvt_pk_bf16_f32 %0, %1, %2" : "=v"(r) : "v"(lo), "v"(hi)); return r; }
; template <int P_>
; __device__ __forceinline__ void dil_wave_unit(LAS unsigned char* wl, const bf16_t* DIL, bf16_t* Y, bf16_t* ST, float* LSE, const float* BT, int b, int h, int r, int nb) {
;     ...
;         for (int e = 0; e < 8; ++e) { const int blk = e >> 2, g = e & 3;
;             float v0 = o[qh][blk][4 * g] * a_cur, v1 = o[qh][blk][4 * g + 1] * a_cur, v2 = o[qh][blk][4 * g + 2] * a_cur, v3 = o[qh][blk][4 * g + 3] * a_cur;
;             if (!first) { v0 += a_prev * bf_lo(pv[qh][e].x); v1 += a_prev * bf_hi(pv[qh][e].x); v2 += a_prev * bf_lo(pv[qh][e].y); v3 += a_prev * bf_hi(pv[qh][e].y); }
;             wv[e].x = cvt_pk_bf16(v0, v1); wv[e].y = cvt_pk_bf16(v2, v3); }
; #pragma unroll
;         for (int e = 0; e < 8; e += 2) { const u32x2 snd = hi ? wv[e] : wv[e + 1]; u32x2 rcv; rcv.x = __shfl_xor(snd.x, 32); rcv.y = __shfl_xor(snd.y, 32);
;             u32x4 o4; if (hi) { o4.x = rcv.x; o4.y = rcv.y; o4.z = wv[e + 1].x; o4.w = wv[e + 1].y; } else { o4.x = wv[e].x; o4.y = wv[e].y; o4.z = rcv.x; o4.w = rcv.y; }
;             *(u32x4*)(ypb + 32 * (e >> 2) + 8 * ((e & 3) + hi)) = o4; }
	v_lshlrev_b32_e32 v42, 16, v86
	v_add_f32_e32 v18, v18, v19
	v_mov_b32_e32 v37, v30
	v_cvt_pk_bf16_f32 v23, v23, v24
	v_cvt_pk_bf16_f32 v24, v25, v18
	v_pk_mul_f32 v[18:19], v[36:37], v[42:43]
	v_and_b32_e32 v42, 0xffff0000, v86
	v_mov_b32_e32 v37, v31
	v_add_f32_e32 v25, v18, v19
	v_pk_mul_f32 v[18:19], v[36:37], v[42:43]
	v_lshlrev_b32_e32 v42, 16, v83
	v_mov_b32_e32 v37, v32
	v_add_f32_e32 v26, v18, v19
	v_pk_mul_f32 v[18:19], v[36:37], v[42:43]
	v_and_b32_e32 v42, 0xffff0000, v83
	v_mov_b32_e32 v37, v33
	v_add_f32_e32 v27, v18, v19
	v_pk_mul_f32 v[18:19], v[36:37], v[42:43]
	v_lshlrev_b32_e32 v42, 16, v88
	v_add_f32_e32 v18, v18, v19
	v_mov_b32_e32 v37, v2
	v_cvt_pk_bf16_f32 v25, v25, v26
	v_cvt_pk_bf16_f32 v26, v27, v18
	v_pk_mul_f32 v[18:19], v[36:37], v[42:43]
	v_and_b32_e32 v42, 0xffff0000, v88
	v_mov_b32_e32 v37, v3
	v_pk_mul_f32 v[2:3], v[36:37], v[42:43]
	v_lshlrev_b32_e32 v42, 16, v85
	v_mov_b32_e32 v37, v4
	v_add_f32_e32 v18, v18, v19
	v_add_f32_e32 v19, v2, v3
	v_pk_mul_f32 v[2:3], v[36:37], v[42:43]
	v_and_b32_e32 v42, 0xffff0000, v85
	v_mov_b32_e32 v37, v5
	v_add_f32_e32 v4, v2, v3
	v_pk_mul_f32 v[2:3], v[36:37], v[42:43]
	v_lshlrev_b32_e32 v42, 16, v82
	v_add_f32_e32 v2, v2, v3
	v_mov_b32_e32 v37, v6
	v_cvt_pk_bf16_f32 v18, v18, v19
	v_cvt_pk_bf16_f32 v19, v4, v2
	v_pk_mul_f32 v[2:3], v[36:37], v[42:43]
	v_and_b32_e32 v42, 0xffff0000, v82
	v_mov_b32_e32 v37, v7
	v_add_f32_e32 v4, v2, v3
	v_pk_mul_f32 v[2:3], v[36:37], v[42:43]
	v_lshlrev_b32_e32 v42, 16, v80
	v_mov_b32_e32 v37, v8
	v_add_f32_e32 v5, v2, v3
	v_pk_mul_f32 v[2:3], v[36:37], v[42:43]
	v_and_b32_e32 v42, 0xffff0000, v80
	v_mov_b32_e32 v37, v9
	v_add_f32_e32 v6, v2, v3
	v_pk_mul_f32 v[2:3], v[36:37], v[42:43]
	v_lshlrev_b32_e32 v42, 16, v84
	v_add_f32_e32 v2, v2, v3
	v_mov_b32_e32 v37, v10
	v_cvt_pk_bf16_f32 v8, v4, v5
	v_cvt_pk_bf16_f32 v9, v6, v2
	v_pk_mul_f32 v[2:3], v[36:37], v[42:43]
	v_and_b32_e32 v42, 0xffff0000, v84
	v_mov_b32_e32 v37, v11
	v_add_f32_e32 v4, v2, v3
	v_pk_mul_f32 v[2:3], v[36:37], v[42:43]
	v_lshlrev_b32_e32 v42, 16, v81
	v_mov_b32_e32 v37, v12
	v_add_f32_e32 v5, v2, v3
	v_pk_mul_f32 v[2:3], v[36:37], v[42:43]
	v_and_b32_e32 v42, 0xffff0000, v81
	v_mov_b32_e32 v37, v13
	v_add_f32_e32 v6, v2, v3
	v_pk_mul_f32 v[2:3], v[36:37], v[42:43]
	v_lshlrev_b32_e32 v42, 16, v79
	v_add_f32_e32 v2, v2, v3
	v_mov_b32_e32 v37, v14
	v_cvt_pk_bf16_f32 v10, v4, v5
	v_cvt_pk_bf16_f32 v11, v6, v2
	v_pk_mul_f32 v[2:3], v[36:37], v[42:43]
	v_and_b32_e32 v42, 0xffff0000, v79
	v_mov_b32_e32 v37, v15
	v_add_f32_e32 v4, v2, v3
	v_pk_mul_f32 v[2:3], v[36:37], v[42:43]
	v_lshlrev_b32_e32 v42, 16, v78
	v_mov_b32_e32 v37, v16
	v_add_f32_e32 v5, v2, v3
	v_pk_mul_f32 v[2:3], v[36:37], v[42:43]
	v_and_b32_e32 v42, 0xffff0000, v78
	v_mov_b32_e32 v37, v17
	v_add_f32_e32 v6, v2, v3
	v_pk_mul_f32 v[2:3], v[36:37], v[42:43]
	v_cvt_pk_bf16_f32 v12, v4, v5
	v_cndmask_b32_e64 v14, v24, v26, s[40:41]
	v_add_f32_e32 v2, v2, v3
	v_cvt_pk_bf16_f32 v13, v6, v2
	v_cndmask_b32_e64 v2, v0, v21, s[40:41]
	v_cndmask_b32_e64 v3, v20, v22, s[40:41]
	ds_bpermute_b32 v2, v208, v2
	ds_bpermute_b32 v3, v208, v3
	v_lshl_add_u64 v[6:7], s[8:9], 0, v[34:35]
	v_cndmask_b32_e64 v15, v23, v25, s[40:41]
	v_lshl_add_u64 v[6:7], v[6:7], 0, v[156:157]
	s_waitcnt lgkmcnt(1)
	v_cndmask_b32_e64 v4, v21, v2, s[40:41]
	v_cndmask_b32_e64 v2, v2, v0, s[40:41]
	s_waitcnt lgkmcnt(0)
	v_cndmask_b32_e64 v5, v22, v3, s[40:41]
	v_cndmask_b32_e64 v3, v3, v20, s[40:41]
	global_store_dwordx4 v[6:7], v[2:5], off offset:1024
	ds_bpermute_b32 v0, v208, v15
	ds_bpermute_b32 v3, v208, v14
	v_cndmask_b32_e64 v14, v19, v9, s[40:41]
	v_cndmask_b32_e64 v15, v18, v8, s[40:41]
	s_andn2_b64 vcc, exec, s[42:43]
	s_waitcnt lgkmcnt(1)
	v_cndmask_b32_e64 v4, v25, v0, s[40:41]
	v_cndmask_b32_e64 v2, v0, v23, s[40:41]
	s_waitcnt lgkmcnt(0)
	v_cndmask_b32_e64 v5, v26, v3, s[40:41]
	v_cndmask_b32_e64 v3, v3, v24, s[40:41]
	global_store_dwordx4 v[6:7], v[2:5], off offset:1056
	ds_bpermute_b32 v0, v208, v15
	ds_bpermute_b32 v3, v208, v14
	v_cndmask_b32_e64 v14, v11, v13, s[40:41]
	v_cndmask_b32_e64 v15, v10, v12, s[40:41]
	s_waitcnt lgkmcnt(1)
	v_cndmask_b32_e64 v4, v8, v0, s[40:41]
	v_cndmask_b32_e64 v2, v0, v18, s[40:41]
	s_waitcnt lgkmcnt(0)
	v_cndmask_b32_e64 v5, v9, v3, s[40:41]
	v_cndmask_b32_e64 v3, v3, v19, s[40:41]
	global_store_dwordx4 v[6:7], v[2:5], off offset:1088
	ds_bpermute_b32 v0, v208, v15
	ds_bpermute_b32 v3, v208, v14
	s_waitcnt lgkmcnt(1)
	v_cndmask_b32_e64 v4, v12, v0, s[40:41]
	v_cndmask_b32_e64 v2, v0, v10, s[40:41]
	s_waitcnt lgkmcnt(0)
	v_cndmask_b32_e64 v5, v13, v3, s[40:41]
	v_cndmask_b32_e64 v3, v3, v11, s[40:41]
	global_store_dwordx4 v[6:7], v[2:5], off offset:1120
	s_cbranch_vccz .LBB0_431
